# grid barrier: non-leader workgroups poll the top generation word directly (one hop less) + attention QK read reorder + far bias hoist
# speedup vs baseline: 1.0073x; 1.0020x over previous
.LBB0_115:
	s_lshl_b32 s4, s33, 8
	s_add_u32 s4, s6, s4
	s_addc_u32 s5, s7, 0
	v_mov_b32_e32 v1, 0x1000
	v_mov_b32_e32 v3, 1
	global_atomic_add v3, v1, v3, s[4:5] offset:1024 sc0
	v_cvt_f32_u32_e32 v1, v2
	v_sub_u32_e32 v4, 0, v2
	v_rcp_iflag_f32_e32 v1, v1
	s_nop 0
	v_mul_f32_e32 v1, 0x4f7ffffe, v1
	v_cvt_u32_f32_e32 v1, v1
	v_mul_lo_u32 v4, v4, v1
	v_mul_hi_u32 v4, v1, v4
	v_add_u32_e32 v1, v1, v4
	s_waitcnt vmcnt(0)
	v_mul_hi_u32 v1, v3, v1
	v_mul_lo_u32 v4, v1, v2
	v_sub_u32_e32 v4, v3, v4
	v_add_u32_e32 v5, 1, v1
	v_cmp_ge_u32_e32 vcc, v4, v2
	v_add_u32_e32 v3, 1, v3
	s_nop 0
	v_cndmask_b32_e32 v1, v1, v5, vcc
	v_sub_u32_e32 v5, v4, v2
	v_cndmask_b32_e32 v4, v4, v5, vcc
	v_add_u32_e32 v5, 1, v1
	v_cmp_ge_u32_e32 vcc, v4, v2
	s_nop 1
	v_cndmask_b32_e32 v1, v1, v5, vcc
	v_mul_lo_u32 v4, v2, v1
	v_add_u32_e32 v2, v4, v2
	v_cmp_ne_u32_e32 vcc, v3, v2
	s_and_saveexec_b64 s[8:9], vcc
	s_xor_b64 s[8:9], exec, s[8:9]
	s_cbranch_execz .LBB0_129
	s_waitcnt lgkmcnt(0)
	v_mov_b32_e32 v0, 0x3000
	global_load_dword v0, v0, s[6:7] offset:1280 sc1
	s_add_u32 s14, s6, 0x3500
	s_addc_u32 s15, s7, 0
	s_waitcnt vmcnt(0)
	v_cmp_eq_u32_e32 vcc, v0, v1
	s_and_saveexec_b64 s[10:11], vcc
	s_cbranch_execz .LBB0_128
	s_load_dwordx4 s[16:19], s[0:1], 0xf0
	s_mov_b32 s26, 1
	s_waitcnt lgkmcnt(0)
	s_mov_b64 s[16:17], 0
	v_mov_b32_e32 v0, 0
	s_add_u32 s12, s18, 0x4200
	s_addc_u32 s13, s19, 0
	s_branch .LBB0_119

.LBB0_367:
	v_readlane_b32 s4, v253, 11
	v_readlane_b32 s5, v253, 12
	v_mov_b32_e32 v1, 1
	v_sub_u32_e32 v4, 0, v2
	s_nop 2
	global_atomic_add v3, v145, v1, s[4:5] sc0
	v_cvt_f32_u32_e32 v1, v2
	v_rcp_iflag_f32_e32 v1, v1
	s_nop 0
	v_mul_f32_e32 v1, 0x4f7ffffe, v1
	v_cvt_u32_f32_e32 v1, v1
	v_mul_lo_u32 v4, v4, v1
	v_mul_hi_u32 v4, v1, v4
	v_add_u32_e32 v1, v1, v4
	s_waitcnt vmcnt(0)
	v_mul_hi_u32 v1, v3, v1
	v_mul_lo_u32 v4, v1, v2
	v_sub_u32_e32 v4, v3, v4
	v_add_u32_e32 v5, 1, v1
	v_cmp_ge_u32_e32 vcc, v4, v2
	v_add_u32_e32 v3, 1, v3
	s_nop 0
	v_cndmask_b32_e32 v1, v1, v5, vcc
	v_sub_u32_e32 v5, v4, v2
	v_cndmask_b32_e32 v4, v4, v5, vcc
	v_add_u32_e32 v5, 1, v1
	v_cmp_ge_u32_e32 vcc, v4, v2
	s_nop 1
	v_cndmask_b32_e32 v1, v1, v5, vcc
	v_mul_lo_u32 v4, v2, v1
	v_add_u32_e32 v2, v4, v2
	v_cmp_ne_u32_e32 vcc, v3, v2
	s_and_saveexec_b64 s[4:5], vcc
	s_xor_b64 s[4:5], exec, s[4:5]
	s_cbranch_execz .LBB0_381
	v_readlane_b32 s6, v253, 17
	v_readlane_b32 s7, v253, 18
	s_waitcnt lgkmcnt(0)
	s_nop 3
	global_load_dword v0, v145, s[6:7] sc1
	s_waitcnt vmcnt(0)
	v_cmp_eq_u32_e32 vcc, v0, v1
	s_and_saveexec_b64 s[6:7], vcc
	s_cbranch_execz .LBB0_380
	s_mov_b32 s17, 1
	s_mov_b64 s[44:45], 0
	s_branch .LBB0_371

.LBB0_373:
	v_readlane_b32 s18, v253, 17
	v_readlane_b32 s19, v253, 18
	s_add_i32 s17, s17, 1
	s_mov_b64 s[68:69], -1
	s_nop 2
	global_load_dword v0, v145, s[18:19] sc1
	s_waitcnt vmcnt(0)
	v_cmp_ne_u32_e32 vcc, v0, v1
	s_orn2_b64 s[52:53], vcc, exec
	s_branch .LBB0_370

.LBB0_1011:
	v_readlane_b32 s4, v253, 11
	v_readlane_b32 s5, v253, 12
	v_mov_b32_e32 v1, 1
	v_sub_u32_e32 v4, 0, v2
	s_nop 2
	global_atomic_add v3, v145, v1, s[4:5] sc0
	v_cvt_f32_u32_e32 v1, v2
	v_rcp_iflag_f32_e32 v1, v1
	s_nop 0
	v_mul_f32_e32 v1, 0x4f7ffffe, v1
	v_cvt_u32_f32_e32 v1, v1
	v_mul_lo_u32 v4, v4, v1
	v_mul_hi_u32 v4, v1, v4
	v_add_u32_e32 v1, v1, v4
	s_waitcnt vmcnt(0)
	v_mul_hi_u32 v1, v3, v1
	v_mul_lo_u32 v4, v1, v2
	v_sub_u32_e32 v4, v3, v4
	v_add_u32_e32 v5, 1, v1
	v_cmp_ge_u32_e32 vcc, v4, v2
	v_add_u32_e32 v3, 1, v3
	s_nop 0
	v_cndmask_b32_e32 v1, v1, v5, vcc
	v_sub_u32_e32 v5, v4, v2
	v_cndmask_b32_e32 v4, v4, v5, vcc
	v_add_u32_e32 v5, 1, v1
	v_cmp_ge_u32_e32 vcc, v4, v2
	s_nop 1
	v_cndmask_b32_e32 v1, v1, v5, vcc
	v_mul_lo_u32 v4, v2, v1
	v_add_u32_e32 v2, v4, v2
	v_cmp_ne_u32_e32 vcc, v3, v2
	s_and_saveexec_b64 s[4:5], vcc
	s_xor_b64 s[4:5], exec, s[4:5]
	s_cbranch_execz .LBB0_1025
	v_readlane_b32 s6, v253, 17
	v_readlane_b32 s7, v253, 18
	s_waitcnt lgkmcnt(0)
	s_nop 3
	global_load_dword v0, v145, s[6:7] sc1
	s_waitcnt vmcnt(0)
	v_cmp_eq_u32_e32 vcc, v0, v1
	s_and_saveexec_b64 s[6:7], vcc
	s_cbranch_execz .LBB0_1024
	s_mov_b32 s17, 1
	s_mov_b64 s[42:43], 0
	s_branch .LBB0_1015

.LBB0_1071:
	v_readlane_b32 s4, v253, 11
	v_readlane_b32 s5, v253, 12
	v_mov_b32_e32 v1, 1
	v_sub_u32_e32 v4, 0, v2
	s_nop 2
	global_atomic_add v3, v145, v1, s[4:5] sc0
	v_cvt_f32_u32_e32 v1, v2
	v_rcp_iflag_f32_e32 v1, v1
	s_nop 0
	v_mul_f32_e32 v1, 0x4f7ffffe, v1
	v_cvt_u32_f32_e32 v1, v1
	v_mul_lo_u32 v4, v4, v1
	v_mul_hi_u32 v4, v1, v4
	v_add_u32_e32 v1, v1, v4
	s_waitcnt vmcnt(0)
	v_mul_hi_u32 v1, v3, v1
	v_mul_lo_u32 v4, v1, v2
	v_sub_u32_e32 v4, v3, v4
	v_add_u32_e32 v5, 1, v1
	v_cmp_ge_u32_e32 vcc, v4, v2
	v_add_u32_e32 v3, 1, v3
	s_nop 0
	v_cndmask_b32_e32 v1, v1, v5, vcc
	v_sub_u32_e32 v5, v4, v2
	v_cndmask_b32_e32 v4, v4, v5, vcc
	v_add_u32_e32 v5, 1, v1
	v_cmp_ge_u32_e32 vcc, v4, v2
	s_nop 1
	v_cndmask_b32_e32 v1, v1, v5, vcc
	v_mul_lo_u32 v4, v2, v1
	v_add_u32_e32 v2, v4, v2
	v_cmp_ne_u32_e32 vcc, v3, v2
	s_and_saveexec_b64 s[4:5], vcc
	s_xor_b64 s[4:5], exec, s[4:5]
	s_cbranch_execz .LBB0_1085
	v_readlane_b32 s6, v253, 17
	v_readlane_b32 s7, v253, 18
	s_waitcnt lgkmcnt(0)
	s_nop 3
	global_load_dword v0, v145, s[6:7] sc1
	s_waitcnt vmcnt(0)
	v_cmp_eq_u32_e32 vcc, v0, v1
	s_and_saveexec_b64 s[6:7], vcc
	s_cbranch_execz .LBB0_1084
	s_mov_b32 s16, 1
	s_mov_b64 s[42:43], 0
	s_branch .LBB0_1075

.LBB0_1077:
	v_readlane_b32 s18, v253, 17
	v_readlane_b32 s19, v253, 18
	s_add_i32 s16, s16, 1
	s_mov_b64 s[52:53], -1
	s_nop 2
	global_load_dword v0, v145, s[18:19] sc1
	s_waitcnt vmcnt(0)
	v_cmp_ne_u32_e32 vcc, v0, v1
	s_orn2_b64 s[46:47], vcc, exec
	s_branch .LBB0_1074

.LBB0_1242:
	v_readlane_b32 s6, v253, 11
	v_mov_b32_e32 v3, 0
	v_mov_b32_e32 v1, 1
	v_readlane_b32 s7, v253, 12
	v_sub_u32_e32 v5, 0, v2
	s_nop 3
	global_atomic_add v4, v3, v1, s[6:7] sc0
	v_cvt_f32_u32_e32 v1, v2
	v_rcp_iflag_f32_e32 v1, v1
	s_nop 0
	v_mul_f32_e32 v1, 0x4f7ffffe, v1
	v_cvt_u32_f32_e32 v1, v1
	v_mul_lo_u32 v5, v5, v1
	v_mul_hi_u32 v5, v1, v5
	v_add_u32_e32 v1, v1, v5
	s_waitcnt vmcnt(0)
	v_mul_hi_u32 v1, v4, v1
	v_mul_lo_u32 v5, v1, v2
	v_sub_u32_e32 v5, v4, v5
	v_add_u32_e32 v6, 1, v1
	v_cmp_ge_u32_e32 vcc, v5, v2
	v_add_u32_e32 v4, 1, v4
	s_nop 0
	v_cndmask_b32_e32 v1, v1, v6, vcc
	v_sub_u32_e32 v6, v5, v2
	v_cndmask_b32_e32 v5, v5, v6, vcc
	v_add_u32_e32 v6, 1, v1
	v_cmp_ge_u32_e32 vcc, v5, v2
	s_nop 1
	v_cndmask_b32_e32 v1, v1, v6, vcc
	v_mul_lo_u32 v5, v2, v1
	v_add_u32_e32 v2, v5, v2
	v_cmp_ne_u32_e32 vcc, v4, v2
	s_and_saveexec_b64 s[6:7], vcc
	s_xor_b64 s[6:7], exec, s[6:7]
	s_cbranch_execz .LBB0_1256
	v_readlane_b32 s8, v253, 17
	v_readlane_b32 s9, v253, 18
	s_waitcnt lgkmcnt(0)
	s_nop 3
	global_load_dword v0, v3, s[8:9] sc1
	s_waitcnt vmcnt(0)
	v_cmp_eq_u32_e32 vcc, v0, v1
	s_and_saveexec_b64 s[8:9], vcc
	s_cbranch_execz .LBB0_1255
	s_mov_b32 s20, 1
	s_mov_b64 s[10:11], 0
	v_mov_b32_e32 v0, 0
	s_branch .LBB0_1246

.LBB0_1248:
	v_readlane_b32 s14, v253, 17
	v_readlane_b32 s15, v253, 18
	s_add_i32 s20, s20, 1
	s_mov_b64 s[16:17], -1
	s_nop 2
	global_load_dword v2, v0, s[14:15] sc1
	s_waitcnt vmcnt(0)
	v_cmp_ne_u32_e32 vcc, v2, v1
	s_orn2_b64 s[14:15], vcc, exec
	s_branch .LBB0_1245

.LBB0_1308:
	v_readlane_b32 s4, v253, 11
	v_mov_b32_e32 v3, 0
	v_mov_b32_e32 v1, 1
	v_readlane_b32 s5, v253, 12
	v_sub_u32_e32 v5, 0, v2
	s_nop 3
	global_atomic_add v4, v3, v1, s[4:5] sc0
	v_cvt_f32_u32_e32 v1, v2
	v_rcp_iflag_f32_e32 v1, v1
	s_nop 0
	v_mul_f32_e32 v1, 0x4f7ffffe, v1
	v_cvt_u32_f32_e32 v1, v1
	v_mul_lo_u32 v5, v5, v1
	v_mul_hi_u32 v5, v1, v5
	v_add_u32_e32 v1, v1, v5
	s_waitcnt vmcnt(0)
	v_mul_hi_u32 v1, v4, v1
	v_mul_lo_u32 v5, v1, v2
	v_sub_u32_e32 v5, v4, v5
	v_add_u32_e32 v6, 1, v1
	v_cmp_ge_u32_e32 vcc, v5, v2
	v_add_u32_e32 v4, 1, v4
	s_nop 0
	v_cndmask_b32_e32 v1, v1, v6, vcc
	v_sub_u32_e32 v6, v5, v2
	v_cndmask_b32_e32 v5, v5, v6, vcc
	v_add_u32_e32 v6, 1, v1
	v_cmp_ge_u32_e32 vcc, v5, v2
	s_nop 1
	v_cndmask_b32_e32 v1, v1, v6, vcc
	v_mul_lo_u32 v5, v2, v1
	v_add_u32_e32 v2, v5, v2
	v_cmp_ne_u32_e32 vcc, v4, v2
	s_and_saveexec_b64 s[4:5], vcc
	s_xor_b64 s[4:5], exec, s[4:5]
	s_cbranch_execz .LBB0_1322
	v_readlane_b32 s6, v253, 17
	v_readlane_b32 s7, v253, 18
	s_waitcnt lgkmcnt(0)
	s_nop 3
	global_load_dword v0, v3, s[6:7] sc1
	s_waitcnt vmcnt(0)
	v_cmp_eq_u32_e32 vcc, v0, v1
	s_and_saveexec_b64 s[6:7], vcc
	s_cbranch_execz .LBB0_1321
	s_mov_b32 s18, 1
	s_mov_b64 s[8:9], 0
	v_mov_b32_e32 v0, 0
	s_branch .LBB0_1312

.LBB0_1314:
	v_readlane_b32 s12, v253, 17
	v_readlane_b32 s13, v253, 18
	s_add_i32 s18, s18, 1
	s_mov_b64 s[14:15], -1
	s_nop 2
	global_load_dword v2, v0, s[12:13] sc1
	s_waitcnt vmcnt(0)
	v_cmp_ne_u32_e32 vcc, v2, v1
	s_orn2_b64 s[12:13], vcc, exec
	s_branch .LBB0_1311

.LBB0_1550:
	v_readlane_b32 s4, v253, 11
	v_readlane_b32 s5, v253, 12
	v_cvt_f32_u32_e32 v0, v3
	v_sub_u32_e32 v5, 0, v3
	v_rcp_iflag_f32_e32 v0, v0
	s_nop 1
	global_atomic_add v4, v1, v252, s[4:5] sc0
	v_mul_f32_e32 v0, 0x4f7ffffe, v0
	v_cvt_u32_f32_e32 v0, v0
	v_mul_lo_u32 v5, v5, v0
	v_mul_hi_u32 v5, v0, v5
	v_add_u32_e32 v0, v0, v5
	s_waitcnt vmcnt(0)
	v_mul_hi_u32 v0, v4, v0
	v_mul_lo_u32 v5, v0, v3
	v_sub_u32_e32 v5, v4, v5
	v_add_u32_e32 v6, 1, v0
	v_cmp_ge_u32_e32 vcc, v5, v3
	v_add_u32_e32 v4, 1, v4
	s_nop 0
	v_cndmask_b32_e32 v0, v0, v6, vcc
	v_sub_u32_e32 v6, v5, v3
	v_cndmask_b32_e32 v5, v5, v6, vcc
	v_add_u32_e32 v6, 1, v0
	v_cmp_ge_u32_e32 vcc, v5, v3
	s_nop 1
	v_cndmask_b32_e32 v0, v0, v6, vcc
	v_mul_lo_u32 v5, v3, v0
	v_add_u32_e32 v3, v5, v3
	v_cmp_ne_u32_e32 vcc, v4, v3
	s_and_saveexec_b64 s[4:5], vcc
	s_xor_b64 s[4:5], exec, s[4:5]
	s_cbranch_execz .LBB0_1564
	v_readlane_b32 s6, v253, 17
	v_readlane_b32 s7, v253, 18
	s_waitcnt lgkmcnt(0)
	s_nop 3
	global_load_dword v2, v1, s[6:7] sc1
	s_waitcnt vmcnt(0)
	v_cmp_eq_u32_e32 vcc, v2, v0
	s_and_saveexec_b64 s[6:7], vcc
	s_cbranch_execz .LBB0_1563
	s_mov_b32 s18, 1
	s_mov_b64 s[8:9], 0
	s_branch .LBB0_1554

.LBB0_1984:
	s_or_b64 exec, exec, s[10:11]
	v_lshlrev_b32_e64 v0, v68, 1
	v_and_b32_e32 v0, v0, v154
	v_lshlrev_b32_e32 v180, 6, v68
	v_cmp_eq_u32_e32 vcc, 0, v0
	v_cmp_ne_u32_e64 s[10:11], 0, v0
	v_sub_u32_e32 v0, s54, v180
	v_sub_u32_e32 v66, s60, v180
	s_movk_i32 s8, 0x7f
	s_lshl_b32 s20, s53, 14
	v_cmp_lt_i32_e64 s[12:13], s8, v0
	v_cmp_gt_i32_e64 s[8:9], 2.0, v66
	s_add_i32 s62, s20, 0
	s_and_b64 s[12:13], s[12:13], s[8:9]
	s_and_saveexec_b64 s[44:45], s[12:13]
	s_xor_b64 s[12:13], exec, s[44:45]
	s_cbranch_execz .LBB0_1988
	v_mov_b32_e32 v0, s52
	ds_read_b32 v0, v0 offset:512
	v_add_u32_e32 v66, s62, v137
	v_add_u32_e32 v74, v66, v138
	v_add_u32_e32 v75, v66, v140
	v_add_u32_e32 v76, v66, v141
	v_add_u32_e32 v77, v66, v142
	ds_read_b128 v[66:69], v74 offset:32768
	ds_read_b128 v[70:73], v74 offset:40960
	ds_read_b128 v[194:197], v75 offset:32768
	ds_read_b128 v[202:205], v75 offset:40960
	ds_read_b128 v[210:213], v76 offset:32768
	ds_read_b128 v[218:221], v76 offset:40960
	ds_read_b128 v[226:229], v77 offset:32768
	ds_read_b128 v[234:237], v77 offset:40960
	ds_read_b128 v[158:161], v74 offset:32896
	ds_read_b128 v[164:167], v74 offset:41088
	ds_read_b128 v[198:201], v75 offset:32896
	ds_read_b128 v[206:209], v75 offset:41088
	ds_read_b128 v[214:217], v76 offset:32896
	ds_read_b128 v[222:225], v76 offset:41088
	ds_read_b128 v[230:233], v77 offset:32896
	ds_read_b128 v[238:241], v77 offset:41088
	s_waitcnt lgkmcnt(8)
	v_mfma_f32_32x32x16_bf16 v[82:97], v[66:69], v[98:101], 0
	v_mfma_f32_32x32x16_bf16 v[66:81], v[70:73], v[98:101], 0
	v_mfma_f32_32x32x16_bf16 v[82:97], v[194:197], v[102:105], v[82:97]
	v_mfma_f32_32x32x16_bf16 v[66:81], v[202:205], v[102:105], v[66:81]
	v_mfma_f32_32x32x16_bf16 v[82:97], v[210:213], v[106:109], v[82:97]
	v_mfma_f32_32x32x16_bf16 v[66:81], v[218:221], v[106:109], v[66:81]
	v_mfma_f32_32x32x16_bf16 v[82:97], v[226:229], v[110:113], v[82:97]
	v_mfma_f32_32x32x16_bf16 v[66:81], v[234:237], v[110:113], v[66:81]
	s_waitcnt lgkmcnt(0)
	v_mfma_f32_32x32x16_bf16 v[82:97], v[158:161], v[114:117], v[82:97]
	v_mfma_f32_32x32x16_bf16 v[66:81], v[164:167], v[114:117], v[66:81]
	v_mfma_f32_32x32x16_bf16 v[82:97], v[198:201], v[118:121], v[82:97]
	v_mfma_f32_32x32x16_bf16 v[66:81], v[206:209], v[118:121], v[66:81]
	v_mfma_f32_32x32x16_bf16 v[82:97], v[214:217], v[122:125], v[82:97]
	v_mfma_f32_32x32x16_bf16 v[66:81], v[222:225], v[122:125], v[66:81]
	v_mfma_f32_32x32x16_bf16 v[82:97], v[230:233], v[126:129], v[82:97]
	v_mfma_f32_32x32x16_bf16 v[66:81], v[238:241], v[126:129], v[66:81]
	v_sub_f32_e32 v0, v0, v153
	v_cndmask_b32_e64 v0, v186, v0, s[10:11]

.LBB0_2001:
	s_lshl_b32 s13, s61, 6
	s_sub_i32 s8, s54, s13
	s_sub_i32 s14, s60, s13
	s_cmpk_lt_i32 s8, 0x80
	s_cselect_b64 s[10:11], -1, 0
	s_cmpk_lt_i32 s14, 0x201
	s_cselect_b64 s[8:9], -1, 0
	s_cmpk_gt_i32 s14, 0x200
	v_add_u32_e32 v66, 0, v133
	s_cselect_b64 s[14:15], -1, 0
	s_or_b64 s[14:15], s[10:11], s[14:15]
	v_add_u32_e32 v66, v66, v137
	s_mov_b64 s[10:11], -1
	s_and_b64 vcc, exec, s[14:15]
	v_add_u32_e32 v153, v66, v138
	v_add_u32_e32 v145, v66, v140
	v_add_u32_e32 v135, v66, v141
	v_add_u32_e32 v134, v66, v142
	s_cbranch_vccnz .LBB0_2003
	v_mov_b32_e32 v154, s52
	ds_read_b32 v154, v154 offset:512
	ds_read_b128 v[66:69], v153 offset:32768
	ds_read_b128 v[70:73], v153 offset:40960
	ds_read_b128 v[190:193], v145 offset:32768
	ds_read_b128 v[198:201], v145 offset:40960
	ds_read_b128 v[206:209], v135 offset:32768
	ds_read_b128 v[214:217], v135 offset:40960
	ds_read_b128 v[222:225], v134 offset:32768
	ds_read_b128 v[230:233], v134 offset:40960
	ds_read_b128 v[156:159], v153 offset:32896
	ds_read_b128 v[164:167], v153 offset:41088
	ds_read_b128 v[194:197], v145 offset:32896
	ds_read_b128 v[202:205], v145 offset:41088
	ds_read_b128 v[210:213], v135 offset:32896
	ds_read_b128 v[218:221], v135 offset:41088
	ds_read_b128 v[226:229], v134 offset:32896
	ds_read_b128 v[234:237], v134 offset:41088
	s_waitcnt lgkmcnt(8)
	v_mfma_f32_32x32x16_bf16 v[82:97], v[66:69], v[98:101], 0
	v_mfma_f32_32x32x16_bf16 v[66:81], v[70:73], v[98:101], 0
	v_mfma_f32_32x32x16_bf16 v[82:97], v[190:193], v[102:105], v[82:97]
	v_mfma_f32_32x32x16_bf16 v[66:81], v[198:201], v[102:105], v[66:81]
	v_mfma_f32_32x32x16_bf16 v[82:97], v[206:209], v[106:109], v[82:97]
	v_mfma_f32_32x32x16_bf16 v[66:81], v[214:217], v[106:109], v[66:81]
	v_mfma_f32_32x32x16_bf16 v[82:97], v[222:225], v[110:113], v[82:97]
	v_mfma_f32_32x32x16_bf16 v[66:81], v[230:233], v[110:113], v[66:81]
	s_waitcnt lgkmcnt(0)
	v_mfma_f32_32x32x16_bf16 v[82:97], v[156:159], v[114:117], v[82:97]
	v_mfma_f32_32x32x16_bf16 v[66:81], v[164:167], v[114:117], v[66:81]
	v_mfma_f32_32x32x16_bf16 v[82:97], v[194:197], v[118:121], v[82:97]
	v_mfma_f32_32x32x16_bf16 v[66:81], v[202:205], v[118:121], v[66:81]
	v_mfma_f32_32x32x16_bf16 v[82:97], v[210:213], v[122:125], v[82:97]
	v_mfma_f32_32x32x16_bf16 v[66:81], v[218:221], v[122:125], v[66:81]
	v_mfma_f32_32x32x16_bf16 v[82:97], v[226:229], v[126:129], v[82:97]
	v_mfma_f32_32x32x16_bf16 v[66:81], v[234:237], v[126:129], v[66:81]
	v_sub_f32_e32 v154, v154, v131
	s_mov_b64 s[10:11], 0

.LBB0_3216:
	v_readlane_b32 s4, v253, 11
	v_readlane_b32 s5, v253, 12
	v_cvt_f32_u32_e32 v0, v3
	v_sub_u32_e32 v5, 0, v3
	v_rcp_iflag_f32_e32 v0, v0
	s_nop 1
	global_atomic_add v4, v1, v252, s[4:5] sc0
	v_mul_f32_e32 v0, 0x4f7ffffe, v0
	v_cvt_u32_f32_e32 v0, v0
	v_mul_lo_u32 v5, v5, v0
	v_mul_hi_u32 v5, v0, v5
	v_add_u32_e32 v0, v0, v5
	s_waitcnt vmcnt(0)
	v_mul_hi_u32 v0, v4, v0
	v_mul_lo_u32 v5, v0, v3
	v_sub_u32_e32 v5, v4, v5
	v_add_u32_e32 v6, 1, v0
	v_cmp_ge_u32_e32 vcc, v5, v3
	v_add_u32_e32 v4, 1, v4
	s_nop 0
	v_cndmask_b32_e32 v0, v0, v6, vcc
	v_sub_u32_e32 v6, v5, v3
	v_cndmask_b32_e32 v5, v5, v6, vcc
	v_add_u32_e32 v6, 1, v0
	v_cmp_ge_u32_e32 vcc, v5, v3
	s_nop 1
	v_cndmask_b32_e32 v0, v0, v6, vcc
	v_mul_lo_u32 v5, v3, v0
	v_add_u32_e32 v3, v5, v3
	v_cmp_ne_u32_e32 vcc, v4, v3
	s_and_saveexec_b64 s[4:5], vcc
	s_xor_b64 s[4:5], exec, s[4:5]
	s_cbranch_execz .LBB0_3230
	v_readlane_b32 s6, v253, 17
	v_readlane_b32 s7, v253, 18
	s_waitcnt lgkmcnt(0)
	s_nop 3
	global_load_dword v2, v1, s[6:7] sc1
	s_waitcnt vmcnt(0)
	v_cmp_eq_u32_e32 vcc, v2, v0
	s_and_saveexec_b64 s[6:7], vcc
	s_cbranch_execz .LBB0_3229
	s_mov_b32 s20, 1
	s_mov_b64 s[10:11], 0
	s_branch .LBB0_3220
